# rotK tab3 + back-edge rotation (7.11): loop control, header scalars and K address VALU moved in front of the step barrier; exit path has its own barrier copy
# baseline (speedup 1.0000x reference)
; #define LAS __attribute__((address_space(3)))
; template <int MODE>
; __device__ __forceinline__ void step64(St& S, const bf16x8 (&qf)[4], int t, int qpos0, bool diag, bool first, float cq, float cfar, const LAS float* tab,
;                                        const LAS unsigned char* buf, unsigned vaddr, int r32, int hi) {
;     ...
;     for (int d0 = 0; d0 < 4; ++d0) { const int o = r32 * 128 + (((d0 * 2 + hi) ^ ((r32 >> 1) & 7)) << 4); ka[d0] = *(const LAS bf16x8*)(buf + o); kc[d0] = *(const LAS bf16x8*)(buf + 4096 + o); }
; template <int MODE> ...
;     ...
;     for (int s = T0; s < T1; ++s) {
;         const int t = SU_T(s);
;         const bool more = (s + 2 < T1);
;         if (more) { glds16(kg + (size_t)SU_T(s + 2) * 4096, kdst + s2); glds16(vg + (size_t)SU_T(s + 2) * 4096, vdst + s2); }
;         LAS unsigned char* buf = ring + s0;
;         if (t >= t_lo && t < t_hi)
;             step64<MODE>(S, qf, t, qpos0, t == t_hi - 1, REV ? (t == t_hi - 1) : (t == t_lo), cq, cfar, tab, buf, (unsigned)(unsigned long)(buf + 8192) + vl, r32, hi);
.LBB0_605:
	s_mov_b32 s50, s0
	s_sub_i32 s34, s41, 8
	s_max_i32 s34, s34, 0
	s_add_i32 s2, s50, 0
	v_add_u32_e32 v0, s2, v152
	v_add_u32_e32 v14, s2, v153
	v_add_u32_e32 v15, s2, v154
	v_add_u32_e32 v234, s2, v155
	s_branch .Lk0_post
.Lk0_norescale:
	s_and_b64 vcc, exec, s[46:47]
	s_cbranch_vccnz .Lk0_w0
	s_waitcnt vmcnt(2) lgkmcnt(0)
	s_branch .Lk0_ctl

; #define LAS __attribute__((address_space(3)))
; template <int MODE> ...
;     ...
;     for (int s = T0; s < T1; ++s) {
;         const int t = SU_T(s);
;         const bool more = (s + 2 < T1);
;         if (more) { glds16(kg + (size_t)SU_T(s + 2) * 4096, kdst + s2); glds16(vg + (size_t)SU_T(s + 2) * 4096, vdst + s2); }
;         LAS unsigned char* buf = ring + s0;
;         if (t >= t_lo && t < t_hi)
;             step64<MODE>(S, qf, t, qpos0, t == t_hi - 1, REV ? (t == t_hi - 1) : (t == t_lo), cq, cfar, tab, buf, (unsigned)(unsigned long)(buf + 8192) + vl, r32, hi);
;         if (more) asm volatile("s_waitcnt vmcnt(2) lgkmcnt(0)\n\ts_barrier" ::: "memory");
;         else      asm volatile("s_waitcnt vmcnt(0) lgkmcnt(0)\n\ts_barrier" ::: "memory");
;         const int sn = s0; s0 = s1; s1 = s2; s2 = sn;
;     }
.Lk0_ctl:
	s_add_i32 s44, s44, 1
	s_sub_i32 s48, s48, 64
	v_lshl_add_u64 v[122:123], v[122:123], 0, s[66:67]
	s_cmp_ge_u32 s44, s15
	v_lshl_add_u64 v[124:125], v[124:125], 0, s[66:67]
	s_cbranch_scc1 .Lk0_exitbar
	s_mov_b32 s0, s45
	s_mov_b32 s45, s49
	s_mov_b32 s49, s50
	s_mov_b32 s50, s0
	s_sub_i32 s34, s41, 8
	s_max_i32 s34, s34, 0
	s_add_i32 s2, s50, 0
	v_add_u32_e32 v0, s2, v152
	v_add_u32_e32 v14, s2, v153
	v_add_u32_e32 v15, s2, v154
	v_add_u32_e32 v234, s2, v155
	s_barrier
.Lk0_post:
	s_cmp_gt_i32 s44, s41
	s_cbranch_scc1 .Lk0_noK
	s_cmp_lt_i32 s44, s34
	s_cbranch_scc1 .Lk0_noK
	ds_read_b128 v[186:189], v0 offset:18432
	ds_read_b128 v[194:197], v14 offset:18432
	ds_read_b128 v[202:205], v15 offset:18432
	ds_read_b128 v[210:213], v234 offset:18432
	ds_read_b128 v[190:193], v0 offset:22528
	ds_read_b128 v[198:201], v14 offset:22528
	ds_read_b128 v[206:209], v15 offset:22528
	ds_read_b128 v[214:217], v234 offset:22528

; template <int MODE>
; __device__ __forceinline__ void step64(St& S, const bf16x8 (&qf)[4], int t, int qpos0, bool diag, bool first, float cq, float cfar, const LAS float* tab,
;                                        const LAS unsigned char* buf, unsigned vaddr, int r32, int hi) {
;     ...
;     if (first || __any(rm > THR)) {
;         const float dl = first ? rm : fmaxf(rm, 0.f); S.m += dl;
;         const float f = first ? 1.0f : __builtin_amdgcn_exp2f(-dl); S.l *= f;
; #pragma unroll
;         for (int r = 0; r < 16; ++r) { sa[r] -= dl; sb[r] -= dl; S.o0[r] *= f; S.o1[r] *= f; }
;     }
; template <int MODE> ...
;     ...
;         if (more) asm volatile("s_waitcnt vmcnt(2) lgkmcnt(0)\n\ts_barrier" ::: "memory");
;         else      asm volatile("s_waitcnt vmcnt(0) lgkmcnt(0)\n\ts_barrier" ::: "memory");
;         const int sn = s0; s0 = s1; s1 = s2; s2 = sn;
;     }
.Lk0_first:
	v_add_f32_e32 v157, v157, v14
	v_sub_f32_e32 v48, v48, v14
	v_sub_f32_e32 v49, v49, v14
	v_sub_f32_e32 v50, v50, v14
	v_sub_f32_e32 v51, v51, v14
	v_sub_f32_e32 v52, v52, v14
	v_sub_f32_e32 v53, v53, v14
	v_sub_f32_e32 v54, v54, v14
	v_sub_f32_e32 v55, v55, v14
	v_sub_f32_e32 v56, v56, v14
	v_sub_f32_e32 v57, v57, v14
	v_sub_f32_e32 v58, v58, v14
	v_sub_f32_e32 v59, v59, v14
	v_sub_f32_e32 v60, v60, v14
	v_sub_f32_e32 v61, v61, v14
	v_sub_f32_e32 v62, v62, v14
	v_sub_f32_e32 v63, v63, v14
	v_sub_f32_e32 v64, v64, v14
	v_sub_f32_e32 v65, v65, v14
	v_sub_f32_e32 v66, v66, v14
	v_sub_f32_e32 v67, v67, v14
	v_sub_f32_e32 v68, v68, v14
	v_sub_f32_e32 v69, v69, v14
	v_sub_f32_e32 v70, v70, v14
	v_sub_f32_e32 v71, v71, v14
	v_sub_f32_e32 v72, v72, v14
	v_sub_f32_e32 v73, v73, v14
	v_sub_f32_e32 v74, v74, v14
	v_sub_f32_e32 v75, v75, v14
	v_sub_f32_e32 v76, v76, v14
	v_sub_f32_e32 v77, v77, v14
	v_sub_f32_e32 v78, v78, v14
	v_sub_f32_e32 v79, v79, v14
	s_branch .Lk0_norescale
.Lk0_exitbar:
	s_barrier

; #define LAS __attribute__((address_space(3)))
; template <int MODE> ...
;     ...
;     for (int s = T0; s < T1; ++s) {
;         const int t = SU_T(s);
;         const bool more = (s + 2 < T1);
;         if (more) { glds16(kg + (size_t)SU_T(s + 2) * 4096, kdst + s2); glds16(vg + (size_t)SU_T(s + 2) * 4096, vdst + s2); }
;         LAS unsigned char* buf = ring + s0;
;         if (t >= t_lo && t < t_hi)
;             step64<MODE>(S, qf, t, qpos0, t == t_hi - 1, REV ? (t == t_hi - 1) : (t == t_lo), cq, cfar, tab, buf, (unsigned)(unsigned long)(buf + 8192) + vl, r32, hi);
.LBB0_636:
	s_cmp_ge_u32 s19, s33
	s_cselect_b64 s[24:25], -1, 0
	s_mov_b32 s11, s0
	s_add_i32 s22, s1, -1
	s_add_i32 s6, s11, 0
	v_add_u32_e32 v0, s6, v143
	v_add_u32_e32 v14, s6, v144
	v_add_u32_e32 v15, s6, v145
	v_add_u32_e32 v151, s6, v146
	s_branch .Lk1_post
.Lk1_norescale:
	s_and_b64 vcc, exec, s[24:25]
	s_cbranch_vccnz .Lk1_w0
	s_waitcnt vmcnt(2) lgkmcnt(0)
	s_branch .Lk1_ctl

; #define LAS __attribute__((address_space(3)))
; template <int MODE> ...
;     ...
;     for (int s = T0; s < T1; ++s) {
;         const int t = SU_T(s);
;         const bool more = (s + 2 < T1);
;         if (more) { glds16(kg + (size_t)SU_T(s + 2) * 4096, kdst + s2); glds16(vg + (size_t)SU_T(s + 2) * 4096, vdst + s2); }
;         LAS unsigned char* buf = ring + s0;
;         if (t >= t_lo && t < t_hi)
;             step64<MODE>(S, qf, t, qpos0, t == t_hi - 1, REV ? (t == t_hi - 1) : (t == t_lo), cq, cfar, tab, buf, (unsigned)(unsigned long)(buf + 8192) + vl, r32, hi);
;         if (more) asm volatile("s_waitcnt vmcnt(2) lgkmcnt(0)\n\ts_barrier" ::: "memory");
;         else      asm volatile("s_waitcnt vmcnt(0) lgkmcnt(0)\n\ts_barrier" ::: "memory");
;         const int sn = s0; s0 = s1; s1 = s2; s2 = sn;
;     }
.Lk1_ctl:
	s_add_i32 s19, s19, 1
	v_lshl_add_u64 v[116:117], v[116:117], 0, s[26:27]
	v_lshl_add_u64 v[118:119], v[118:119], 0, s[26:27]
	s_cmp_lg_u32 s22, 0
	v_add_u32_e32 v148, 0xffffff00, v148
	s_cbranch_scc0 .Lk1_exitbar
	s_mov_b32 s1, s22
	s_mov_b32 s0, s10
	s_mov_b32 s10, s12
	s_mov_b32 s12, s11
	s_cmp_ge_u32 s19, s33
	s_cselect_b64 s[24:25], -1, 0
	s_mov_b32 s11, s0
	s_add_i32 s22, s1, -1
	s_add_i32 s6, s11, 0
	v_add_u32_e32 v0, s6, v143
	v_add_u32_e32 v14, s6, v144
	v_add_u32_e32 v15, s6, v145
	v_add_u32_e32 v151, s6, v146
	s_barrier
.Lk1_post:
	s_cmp_gt_i32 s22, s28
	s_cbranch_scc1 .Lk1_noK
	ds_read_b128 v[186:189], v0 offset:18432
	ds_read_b128 v[194:197], v14 offset:18432
	ds_read_b128 v[202:205], v15 offset:18432
	ds_read_b128 v[210:213], v151 offset:18432
	ds_read_b128 v[190:193], v0 offset:22528
	ds_read_b128 v[198:201], v14 offset:22528
	ds_read_b128 v[206:209], v15 offset:22528
	ds_read_b128 v[214:217], v151 offset:22528

; template <int MODE>
; __device__ __forceinline__ void step64(St& S, const bf16x8 (&qf)[4], int t, int qpos0, bool diag, bool first, float cq, float cfar, const LAS float* tab,
;                                        const LAS unsigned char* buf, unsigned vaddr, int r32, int hi) {
;     ...
;     if (first || __any(rm > THR)) {
;         const float dl = first ? rm : fmaxf(rm, 0.f); S.m += dl;
;         const float f = first ? 1.0f : __builtin_amdgcn_exp2f(-dl); S.l *= f;
; #pragma unroll
;         for (int r = 0; r < 16; ++r) { sa[r] -= dl; sb[r] -= dl; S.o0[r] *= f; S.o1[r] *= f; }
;     }
.Lk1_first:
	v_add_f32_e32 v150, v150, v14
	v_sub_f32_e32 v48, v48, v14
	v_sub_f32_e32 v49, v49, v14
	v_sub_f32_e32 v50, v50, v14
	v_sub_f32_e32 v51, v51, v14
	v_sub_f32_e32 v52, v52, v14
	v_sub_f32_e32 v53, v53, v14
	v_sub_f32_e32 v54, v54, v14
	v_sub_f32_e32 v55, v55, v14
	v_sub_f32_e32 v56, v56, v14
	v_sub_f32_e32 v57, v57, v14
	v_sub_f32_e32 v58, v58, v14
	v_sub_f32_e32 v59, v59, v14
	v_sub_f32_e32 v60, v60, v14
	v_sub_f32_e32 v61, v61, v14
	v_sub_f32_e32 v62, v62, v14
	v_sub_f32_e32 v63, v63, v14
	v_sub_f32_e32 v64, v64, v14
	v_sub_f32_e32 v65, v65, v14
	v_sub_f32_e32 v66, v66, v14
	v_sub_f32_e32 v67, v67, v14
	v_sub_f32_e32 v68, v68, v14
	v_sub_f32_e32 v69, v69, v14
	v_sub_f32_e32 v70, v70, v14
	v_sub_f32_e32 v71, v71, v14
	v_sub_f32_e32 v72, v72, v14
	v_sub_f32_e32 v73, v73, v14
	v_sub_f32_e32 v74, v74, v14
	v_sub_f32_e32 v75, v75, v14
	v_sub_f32_e32 v76, v76, v14
	v_sub_f32_e32 v77, v77, v14
	v_sub_f32_e32 v78, v78, v14
	v_sub_f32_e32 v79, v79, v14
	s_branch .Lk1_norescale
